# v9 with cross-unit prefetch of the SwiGLU row scales: next unit's row partials loaded during the current epilogue, reduced at its end, carried through the K loop in v250/v251
# speedup vs baseline: 1.0001x; 1.0001x over previous
.LBB0_906:
	s_mov_b32 s98, 0
	s_cmp_lt_i32 s26, 6
	s_cselect_b64 s[10:11], -1, 0
	s_and_b64 s[0:1], s[10:11], s[0:1]
	v_readlane_b32 s70, v249, 45
	s_andn2_b64 vcc, exec, s[0:1]
	v_readlane_b32 s71, v249, 46
	s_cbranch_vccnz .LBB0_928
	s_cmpk_gt_i32 s2, 0xb57
	v_mov_b32_e32 v12, v184
	s_movk_i32 s4, 0x400
	s_cbranch_scc1 .LBB0_928
	v_lshl_add_u32 v0, v12, 4, s31
	v_add_u32_e32 v1, 0x2000, v0
	v_ashrrev_i32_e32 v2, 31, v1
	v_lshrrev_b32_e32 v2, 22, v2
	v_add_u32_e32 v2, v1, v2
	v_ashrrev_i32_e32 v2, 10, v2
	v_mul_i32_i24_e32 v3, 0x400, v2
	v_sub_u32_e32 v1, v1, v3
	v_lshrrev_b32_e32 v3, 4, v1
	v_bitop3_b32 v1, v3, v1, 32 bitop3:0x6c
	v_ashrrev_i32_e32 v3, 31, v1
	v_lshrrev_b32_e32 v3, 26, v3
	v_add_u32_e32 v3, v1, v3
	v_lshlrev_b32_e32 v5, 3, v2
	v_lshlrev_b32_e32 v2, 5, v2
	v_and_b32_e32 v13, 32, v2
	v_and_b32_e32 v2, 0xffc0, v3
	v_sub_u32_e32 v1, v1, v2
	v_ashrrev_i32_e32 v4, 6, v3
	v_and_b32_e32 v5, -16, v5
	v_lshrrev_b16_e32 v2, 7, v1
	v_add_u32_e32 v5, v4, v5
	v_and_b32_e32 v2, 1, v2
	v_and_b32_e32 v4, 3, v4
	s_mov_b32 s0, 0x7fffffe0
	v_lshrrev_b32_e32 v6, 2, v5
	v_lshlrev_b32_e32 v7, 1, v5
	v_add_u16_e32 v1, v1, v2
	v_mov_b32_e32 v2, 1
	v_and_or_b32 v4, v5, s0, v4
	v_and_b32_e32 v6, 4, v6
	v_and_b32_e32 v7, 24, v7
	v_ashrrev_i16_sdwa v1, v2, sext(v1) dst_sel:DWORD dst_unused:UNUSED_PAD src0_sel:DWORD src1_sel:BYTE_0
	v_or3_b32 v4, v4, v6, v7
	v_bfe_i32 v14, v1, 0, 16
	v_mul_lo_u32 v4, v4, s4
	v_add_u32_e32 v1, v13, v14
	v_mul_lo_u32 v15, v5, s4
	v_add_lshl_u32 v128, v4, v1, 1
	v_add_lshl_u32 v130, v1, v15, 1
	v_ashrrev_i32_e32 v1, 31, v0
	v_lshrrev_b32_e32 v1, 22, v1
	v_add_u32_e32 v1, v0, v1
	v_ashrrev_i32_e32 v1, 10, v1
	v_mul_i32_i24_e32 v3, 0x400, v1
	v_sub_u32_e32 v0, v0, v3
	v_lshrrev_b32_e32 v3, 4, v0
	v_bitop3_b32 v0, v3, v0, 32 bitop3:0x6c
	v_ashrrev_i32_e32 v3, 31, v0
	v_lshrrev_b32_e32 v3, 26, v3
	v_add_u32_e32 v3, v0, v3
	v_lshlrev_b32_e32 v5, 3, v1
	v_ashrrev_i32_e32 v4, 6, v3
	v_and_b32_e32 v5, -16, v5
	v_add_u32_e32 v5, v4, v5
	v_and_b32_e32 v4, 3, v4
	s_ashr_i32 s5, s4, 31
	v_and_or_b32 v4, v5, s0, v4
	v_readlane_b32 s0, v248, 20
	s_lshl_b64 s[16:17], s[4:5], 8
	s_lshl_b64 s[18:19], s[4:5], 9
	v_readlane_b32 s1, v248, 21
	s_movk_i32 s3, 0x16c
	s_and_b64 s[0:1], s[0:1], exec
	s_cselect_b32 s0, s3, 0x16b
	v_readlane_b32 s1, v248, 22
	s_mul_i32 s0, s1, s0
	v_readlane_b32 s1, v248, 19
	s_add_i32 s0, s0, s1
	s_mul_hi_i32 s1, s0, 0x2e8ba2e9
	s_lshr_b32 s6, s1, 31
	s_ashr_i32 s1, s1, 5
	s_add_i32 s1, s1, s6
	v_lshlrev_b32_e32 v1, 5, v1
	s_lshl_b32 s7, s1, 3
	v_and_b32_e32 v16, 32, v1
	v_and_b32_e32 v1, 0xc0, v3
	s_sub_i32 s6, 0x84, s7
	v_sub_u32_e32 v0, v0, v1
	s_min_u32 s8, s6, 8
	s_mulk_i32 s1, 0xb0
	v_ashrrev_i16_sdwa v0, v2, sext(v0) dst_sel:DWORD dst_unused:UNUSED_PAD src0_sel:DWORD src1_sel:BYTE_0
	s_sub_i32 s9, s0, s1
	v_cvt_f32_ubyte0_e32 v2, s8
	v_lshrrev_b32_e32 v6, 2, v5
	v_lshlrev_b32_e32 v7, 1, v5
	v_cvt_f32_i32_e32 v1, s9
	v_rcp_iflag_f32_e32 v3, v2
	v_and_b32_e32 v6, 4, v6
	v_and_b32_e32 v7, 24, v7
	v_or3_b32 v4, v4, v6, v7
	v_bfe_i32 v17, v0, 0, 16
	v_mul_lo_u32 v4, v4, s4
	v_add_u32_e32 v0, v16, v17
	v_mul_lo_u32 v18, v5, s4
	v_add_lshl_u32 v132, v4, v0, 1
	v_add_lshl_u32 v134, v0, v18, 1
	v_mul_f32_e32 v0, v1, v3
	v_trunc_f32_e32 v0, v0
	v_fma_f32 v1, -v0, v2, v1
	v_cvt_i32_f32_e32 v0, v0
	s_ashr_i32 s0, s9, 30
	s_or_b32 s6, s0, 1
	v_cmp_ge_f32_e64 s[0:1], |v1|, v2
	s_and_b64 s[0:1], s[0:1], exec
	s_cselect_b32 s0, s6, 0
	v_readfirstlane_b32 s1, v0
	s_add_i32 s6, s1, s0
	s_mul_i32 s0, s6, s8
	s_sub_i32 s0, s9, s0
	s_sext_i32_i16 s0, s0
	s_add_i32 s59, s7, s0
	s_ashr_i32 s0, s59, 31
	s_mul_i32 s0, s18, s0
	s_mul_hi_u32 s1, s18, s59
	s_add_i32 s7, s1, s0
	s_lshr_b64 s[0:1], s[4:5], 23
	s_mul_i32 s1, s0, s59
	s_add_i32 s7, s7, s1
	s_bfe_i64 s[8:9], s[6:7], 0x100000
	s_mul_i32 s1, s18, s9
	s_mul_hi_u32 s9, s18, s8
	s_add_i32 s1, s9, s1
	s_mul_i32 s0, s0, s8
	s_add_i32 s1, s1, s0
	s_mul_i32 s0, s18, s8
	v_readlane_b32 s8, v249, 47
	v_readlane_b32 s9, v249, 48
	s_add_u32 s42, s8, s0
	s_addc_u32 s43, s9, s1
	s_add_i32 s28, s31, 0
	s_add_i32 m0, s28, 0x10000
	s_mul_i32 s33, s18, s59
	global_load_lds_dwordx4 v132, s[42:43]
	s_add_i32 m0, s28, 0x12000
	s_add_u32 s0, s42, s16
	global_load_lds_dwordx4 v128, s[42:43]
	s_addc_u32 s1, s43, s17
	s_add_i32 m0, s28, 0x14000
	v_mov_b32_e32 v133, 0
	global_load_lds_dwordx4 v132, s[0:1]
	s_add_i32 m0, s28, 0x16000
	s_add_u32 s40, s34, s33
	s_addc_u32 s41, s35, s7
	s_add_i32 s33, s28, 0x2000
	global_load_lds_dwordx4 v128, s[0:1]
	s_mov_b32 m0, s28
	s_add_u32 s8, s40, s16
	global_load_lds_dwordx4 v134, s[40:41]
	s_mov_b32 m0, s33
	s_addc_u32 s9, s41, s17
	s_add_i32 s44, s28, 0x4000
	global_load_lds_dwordx4 v130, s[40:41]
	s_mov_b32 m0, s44
	s_add_i32 s45, s28, 0x6000
	global_load_lds_dwordx4 v134, s[8:9]
	s_mov_b32 m0, s45
	v_mov_b32_e32 v129, v133
	global_load_lds_dwordx4 v130, s[8:9]
	v_readlane_b32 s8, v248, 26
	v_readlane_b32 s9, v248, 27
	v_mov_b32_e32 v135, v133
	v_mov_b32_e32 v131, v133
	v_cndmask_b32_e64 v10, 0, 1, s[8:9]
	s_mov_b32 s46, 0
	v_lshl_add_u64 v[8:9], s[42:43], 0, v[132:133]
	v_lshl_add_u64 v[4:5], s[42:43], 0, v[128:129]
	v_lshl_add_u64 v[2:3], s[0:1], 0, v[132:133]
	v_lshl_add_u64 v[0:1], s[0:1], 0, v[128:129]
	v_lshl_add_u64 v[6:7], s[40:41], 0, v[134:135]
	v_cmp_ne_u32_e64 s[0:1], 1, v10
	s_andn2_b64 vcc, exec, s[8:9]
	v_lshl_add_u64 v[10:11], s[40:41], 0, v[130:131]
	s_cbranch_vccnz .LBB0_910
	s_barrier

.LBB0_922:
	v_lshl_add_u32 v148, s59, 8, v150
	v_lshrrev_b32_e32 v144, 4, v184
	s_cmp_eq_u32 s98, 0
	s_cbranch_scc0 .Le5_skipld
	v_lshl_add_u32 v145, v144, 4, v148
	v_lshlrev_b32_e32 v146, 6, v145
	v_add_u32_e32 v147, 0x2000, v146
	global_load_dwordx4 v[186:189], v146, s[14:15] offset:0
	global_load_dwordx4 v[190:193], v146, s[14:15] offset:16
	global_load_dwordx4 v[194:197], v146, s[14:15] offset:32
	global_load_dwordx4 v[198:201], v146, s[14:15] offset:48
	global_load_dwordx4 v[202:205], v147, s[14:15] offset:0
	global_load_dwordx4 v[206:209], v147, s[14:15] offset:16
	global_load_dwordx4 v[210:213], v147, s[14:15] offset:32
	global_load_dwordx4 v[214:217], v147, s[14:15] offset:48

.LBB0_924:
	v_and_b32_e32 v157, 15, v184
	v_lshlrev_b32_e32 v157, 2, v157
	v_mov_b32_e32 v160, v157
	v_add_u32_e32 v161, 64, v157
	v_add_u32_e32 v162, 128, v157
	v_add_u32_e32 v163, 192, v157
	s_and_b64 vcc, exec, s[4:5]
	s_cmp_eq_u32 s98, 0
	s_cbranch_scc0 .Le5_havers
	s_waitcnt vmcnt(0)
	v_add_f32_e32 v186, v186, v187
	v_add_f32_e32 v188, v188, v189
	v_add_f32_e32 v190, v190, v191
	v_add_f32_e32 v192, v192, v193
	v_add_f32_e32 v194, v194, v195
	v_add_f32_e32 v196, v196, v197
	v_add_f32_e32 v198, v198, v199
	v_add_f32_e32 v200, v200, v201
	v_add_f32_e32 v186, v186, v188
	v_add_f32_e32 v190, v190, v192
	v_add_f32_e32 v194, v194, v196
	v_add_f32_e32 v198, v198, v200
	v_add_f32_e32 v158, v186, v190
	v_add_f32_e32 v158, v158, v194
	v_add_f32_e32 v158, v158, v198
	v_fmamk_f32 v158, v158, 0x3a800000, v156
	v_add_f32_e32 v202, v202, v203
	v_add_f32_e32 v204, v204, v205
	v_add_f32_e32 v206, v206, v207
	v_add_f32_e32 v208, v208, v209
	v_add_f32_e32 v210, v210, v211
	v_add_f32_e32 v212, v212, v213
	v_add_f32_e32 v214, v214, v215
	v_add_f32_e32 v216, v216, v217
	v_add_f32_e32 v202, v202, v204
	v_add_f32_e32 v206, v206, v208
	v_add_f32_e32 v210, v210, v212
	v_add_f32_e32 v214, v214, v216
	v_add_f32_e32 v159, v202, v206
	v_add_f32_e32 v159, v159, v210
	v_add_f32_e32 v159, v159, v214
	v_fmamk_f32 v159, v159, 0x3a800000, v156
	v_rsq_f32_e32 v158, v158
	v_rsq_f32_e32 v159, v159
	s_branch .Le5_rsdone
.Le5_havers:
	v_mov_b32_e32 v158, v250
	v_mov_b32_e32 v159, v251
.Le5_rsdone:
	v_lshl_add_u32 v203, s60, 7, v152
	v_lshlrev_b32_e32 v203, 1, v203
	v_mad_u32_u24 v202, v148, s52, v203
	ds_bpermute_b32 v164, v160, v158
	ds_bpermute_b32 v166, v161, v158
	ds_bpermute_b32 v168, v162, v158
	ds_bpermute_b32 v170, v163, v158
	ds_bpermute_b32 v172, v160, v159
	ds_bpermute_b32 v174, v161, v159
	ds_bpermute_b32 v176, v162, v159
	ds_bpermute_b32 v178, v163, v159
	v_mov_b32_e32 v204, v202
	v_add_u32_e32 v205, 0x16000, v202
	v_add_u32_e32 v206, 0x2c000, v202
	v_add_u32_e32 v207, 0x42000, v202
	v_add_u32_e32 v208, 0xb0000, v202
	v_add_u32_e32 v209, 0xc6000, v202
	v_add_u32_e32 v210, 0xdc000, v202
	v_add_u32_e32 v211, 0xf2000, v202
	s_mov_b32 s98, 0
	s_cmp_eq_u64 s[4:5], 0
	s_cbranch_scc0 .Le5_nonext
	v_lshl_add_u32 v216, s58, 8, v150
	v_lshl_add_u32 v216, v144, 4, v216
	v_lshlrev_b32_e32 v216, 6, v216
	v_add_u32_e32 v217, 0x2000, v216
	global_load_dwordx4 v[224:227], v216, s[14:15] offset:0
	global_load_dwordx4 v[228:231], v216, s[14:15] offset:16
	global_load_dwordx4 v[232:235], v216, s[14:15] offset:32
	global_load_dwordx4 v[236:239], v216, s[14:15] offset:48
	global_load_dwordx4 v[240:243], v217, s[14:15] offset:0
	global_load_dwordx4 v[244:247], v217, s[14:15] offset:16
	global_load_dwordx4 v[180:183], v217, s[14:15] offset:32
	global_load_dwordx4 v[212:215], v217, s[14:15] offset:48
	s_mov_b32 s98, 1
.Le5_nonext:
	s_waitcnt lgkmcnt(7)
	v_pk_mul_f32 v[120:121], v[120:121], v[164:165] op_sel_hi:[1,0]
	v_pk_mul_f32 v[122:123], v[122:123], v[164:165] op_sel_hi:[1,0]
	v_pk_mul_f32 v[116:117], v[116:117], v[164:165] op_sel_hi:[1,0]
	v_pk_mul_f32 v[118:119], v[118:119], v[164:165] op_sel_hi:[1,0]
	v_pk_mul_f32 v[124:125], v[124:125], v[164:165] op_sel_hi:[1,0]
	v_pk_mul_f32 v[126:127], v[126:127], v[164:165] op_sel_hi:[1,0]
	v_pk_mul_f32 v[112:113], v[112:113], v[164:165] op_sel_hi:[1,0]
	v_pk_mul_f32 v[114:115], v[114:115], v[164:165] op_sel_hi:[1,0]
	v_mul_f32_e32 v186, 0xbfb8aa3b, v120
	v_mul_f32_e32 v187, 0xbfb8aa3b, v121
	v_mul_f32_e32 v188, 0xbfb8aa3b, v122
	v_mul_f32_e32 v189, 0xbfb8aa3b, v123
	v_mul_f32_e32 v190, 0xbfb8aa3b, v116
	v_mul_f32_e32 v191, 0xbfb8aa3b, v117
	v_mul_f32_e32 v192, 0xbfb8aa3b, v118
	v_mul_f32_e32 v193, 0xbfb8aa3b, v119
	v_exp_f32_e32 v186, v186
	v_exp_f32_e32 v187, v187
	v_exp_f32_e32 v188, v188
	v_exp_f32_e32 v189, v189
	v_exp_f32_e32 v190, v190
	v_exp_f32_e32 v191, v191
	v_exp_f32_e32 v192, v192
	v_exp_f32_e32 v193, v193
	v_add_f32_e32 v186, 1.0, v186
	v_add_f32_e32 v187, 1.0, v187
	v_add_f32_e32 v188, 1.0, v188
	v_add_f32_e32 v189, 1.0, v189
	v_add_f32_e32 v190, 1.0, v190
	v_add_f32_e32 v191, 1.0, v191
	v_add_f32_e32 v192, 1.0, v192
	v_add_f32_e32 v193, 1.0, v193
	v_rcp_f32_e32 v186, v186
	v_rcp_f32_e32 v187, v187
	v_rcp_f32_e32 v188, v188
	v_rcp_f32_e32 v189, v189
	v_rcp_f32_e32 v190, v190
	v_rcp_f32_e32 v191, v191
	v_rcp_f32_e32 v192, v192
	v_rcp_f32_e32 v193, v193
	v_pk_mul_f32 v[120:121], v[120:121], v[186:187]
	v_pk_mul_f32 v[122:123], v[122:123], v[188:189]
	v_pk_mul_f32 v[116:117], v[116:117], v[190:191]
	v_pk_mul_f32 v[118:119], v[118:119], v[192:193]
	v_pk_mul_f32 v[120:121], v[124:125], v[120:121]
	v_pk_mul_f32 v[122:123], v[126:127], v[122:123]
	v_pk_mul_f32 v[116:117], v[112:113], v[116:117]
	v_pk_mul_f32 v[118:119], v[114:115], v[118:119]
	v_cvt_pk_bf16_f32 v112, v120, v121
	v_cvt_pk_bf16_f32 v113, v122, v123
	v_cvt_pk_bf16_f32 v114, v116, v117
	v_cvt_pk_bf16_f32 v115, v118, v119
	global_store_dwordx4 v204, v[112:115], s[82:83]
	s_waitcnt lgkmcnt(6)
	v_pk_mul_f32 v[108:109], v[108:109], v[166:167] op_sel_hi:[1,0]
	v_pk_mul_f32 v[110:111], v[110:111], v[166:167] op_sel_hi:[1,0]
	v_pk_mul_f32 v[100:101], v[100:101], v[166:167] op_sel_hi:[1,0]
	v_pk_mul_f32 v[102:103], v[102:103], v[166:167] op_sel_hi:[1,0]
	v_pk_mul_f32 v[104:105], v[104:105], v[166:167] op_sel_hi:[1,0]
	v_pk_mul_f32 v[106:107], v[106:107], v[166:167] op_sel_hi:[1,0]
	v_pk_mul_f32 v[96:97], v[96:97], v[166:167] op_sel_hi:[1,0]
	v_pk_mul_f32 v[98:99], v[98:99], v[166:167] op_sel_hi:[1,0]
	v_mul_f32_e32 v194, 0xbfb8aa3b, v108
	v_mul_f32_e32 v195, 0xbfb8aa3b, v109
	v_mul_f32_e32 v196, 0xbfb8aa3b, v110
	v_mul_f32_e32 v197, 0xbfb8aa3b, v111
	v_mul_f32_e32 v198, 0xbfb8aa3b, v100
	v_mul_f32_e32 v199, 0xbfb8aa3b, v101
	v_mul_f32_e32 v200, 0xbfb8aa3b, v102
	v_mul_f32_e32 v201, 0xbfb8aa3b, v103
	v_exp_f32_e32 v194, v194
	v_exp_f32_e32 v195, v195
	v_exp_f32_e32 v196, v196
	v_exp_f32_e32 v197, v197
	v_exp_f32_e32 v198, v198
	v_exp_f32_e32 v199, v199
	v_exp_f32_e32 v200, v200
	v_exp_f32_e32 v201, v201
	v_add_f32_e32 v194, 1.0, v194
	v_add_f32_e32 v195, 1.0, v195
	v_add_f32_e32 v196, 1.0, v196
	v_add_f32_e32 v197, 1.0, v197
	v_add_f32_e32 v198, 1.0, v198
	v_add_f32_e32 v199, 1.0, v199
	v_add_f32_e32 v200, 1.0, v200
	v_add_f32_e32 v201, 1.0, v201
	v_rcp_f32_e32 v194, v194
	v_rcp_f32_e32 v195, v195
	v_rcp_f32_e32 v196, v196
	v_rcp_f32_e32 v197, v197
	v_rcp_f32_e32 v198, v198
	v_rcp_f32_e32 v199, v199
	v_rcp_f32_e32 v200, v200
	v_rcp_f32_e32 v201, v201
	v_pk_mul_f32 v[108:109], v[108:109], v[194:195]
	v_pk_mul_f32 v[110:111], v[110:111], v[196:197]
	v_pk_mul_f32 v[100:101], v[100:101], v[198:199]
	v_pk_mul_f32 v[102:103], v[102:103], v[200:201]
	v_pk_mul_f32 v[108:109], v[104:105], v[108:109]
	v_pk_mul_f32 v[110:111], v[106:107], v[110:111]
	v_pk_mul_f32 v[100:101], v[96:97], v[100:101]
	v_pk_mul_f32 v[102:103], v[98:99], v[102:103]
	v_cvt_pk_bf16_f32 v96, v108, v109
	v_cvt_pk_bf16_f32 v97, v110, v111
	v_cvt_pk_bf16_f32 v98, v100, v101
	v_cvt_pk_bf16_f32 v99, v102, v103
	global_store_dwordx4 v205, v[96:99], s[82:83]
	s_waitcnt lgkmcnt(5)
	v_pk_mul_f32 v[92:93], v[92:93], v[168:169] op_sel_hi:[1,0]
	v_pk_mul_f32 v[94:95], v[94:95], v[168:169] op_sel_hi:[1,0]
	v_pk_mul_f32 v[84:85], v[84:85], v[168:169] op_sel_hi:[1,0]
	v_pk_mul_f32 v[86:87], v[86:87], v[168:169] op_sel_hi:[1,0]
	v_pk_mul_f32 v[88:89], v[88:89], v[168:169] op_sel_hi:[1,0]
	v_pk_mul_f32 v[90:91], v[90:91], v[168:169] op_sel_hi:[1,0]
	v_pk_mul_f32 v[80:81], v[80:81], v[168:169] op_sel_hi:[1,0]
	v_pk_mul_f32 v[82:83], v[82:83], v[168:169] op_sel_hi:[1,0]
	v_mul_f32_e32 v186, 0xbfb8aa3b, v92
	v_mul_f32_e32 v187, 0xbfb8aa3b, v93
	v_mul_f32_e32 v188, 0xbfb8aa3b, v94
	v_mul_f32_e32 v189, 0xbfb8aa3b, v95
	v_mul_f32_e32 v190, 0xbfb8aa3b, v84
	v_mul_f32_e32 v191, 0xbfb8aa3b, v85
	v_mul_f32_e32 v192, 0xbfb8aa3b, v86
	v_mul_f32_e32 v193, 0xbfb8aa3b, v87
	v_exp_f32_e32 v186, v186
	v_exp_f32_e32 v187, v187
	v_exp_f32_e32 v188, v188
	v_exp_f32_e32 v189, v189
	v_exp_f32_e32 v190, v190
	v_exp_f32_e32 v191, v191
	v_exp_f32_e32 v192, v192
	v_exp_f32_e32 v193, v193
	v_add_f32_e32 v186, 1.0, v186
	v_add_f32_e32 v187, 1.0, v187
	v_add_f32_e32 v188, 1.0, v188
	v_add_f32_e32 v189, 1.0, v189
	v_add_f32_e32 v190, 1.0, v190
	v_add_f32_e32 v191, 1.0, v191
	v_add_f32_e32 v192, 1.0, v192
	v_add_f32_e32 v193, 1.0, v193
	v_rcp_f32_e32 v186, v186
	v_rcp_f32_e32 v187, v187
	v_rcp_f32_e32 v188, v188
	v_rcp_f32_e32 v189, v189
	v_rcp_f32_e32 v190, v190
	v_rcp_f32_e32 v191, v191
	v_rcp_f32_e32 v192, v192
	v_rcp_f32_e32 v193, v193
	v_pk_mul_f32 v[92:93], v[92:93], v[186:187]
	v_pk_mul_f32 v[94:95], v[94:95], v[188:189]
	v_pk_mul_f32 v[84:85], v[84:85], v[190:191]
	v_pk_mul_f32 v[86:87], v[86:87], v[192:193]
	v_pk_mul_f32 v[92:93], v[88:89], v[92:93]
	v_pk_mul_f32 v[94:95], v[90:91], v[94:95]
	v_pk_mul_f32 v[84:85], v[80:81], v[84:85]
	v_pk_mul_f32 v[86:87], v[82:83], v[86:87]
	v_cvt_pk_bf16_f32 v80, v92, v93
	v_cvt_pk_bf16_f32 v81, v94, v95
	v_cvt_pk_bf16_f32 v82, v84, v85
	v_cvt_pk_bf16_f32 v83, v86, v87
	global_store_dwordx4 v206, v[80:83], s[82:83]
	s_waitcnt lgkmcnt(4)
	v_pk_mul_f32 v[76:77], v[76:77], v[170:171] op_sel_hi:[1,0]
	v_pk_mul_f32 v[78:79], v[78:79], v[170:171] op_sel_hi:[1,0]
	v_pk_mul_f32 v[68:69], v[68:69], v[170:171] op_sel_hi:[1,0]
	v_pk_mul_f32 v[70:71], v[70:71], v[170:171] op_sel_hi:[1,0]
	v_pk_mul_f32 v[72:73], v[72:73], v[170:171] op_sel_hi:[1,0]
	v_pk_mul_f32 v[74:75], v[74:75], v[170:171] op_sel_hi:[1,0]
	v_pk_mul_f32 v[64:65], v[64:65], v[170:171] op_sel_hi:[1,0]
	v_pk_mul_f32 v[66:67], v[66:67], v[170:171] op_sel_hi:[1,0]
	v_mul_f32_e32 v194, 0xbfb8aa3b, v76
	v_mul_f32_e32 v195, 0xbfb8aa3b, v77
	v_mul_f32_e32 v196, 0xbfb8aa3b, v78
	v_mul_f32_e32 v197, 0xbfb8aa3b, v79
	v_mul_f32_e32 v198, 0xbfb8aa3b, v68
	v_mul_f32_e32 v199, 0xbfb8aa3b, v69
	v_mul_f32_e32 v200, 0xbfb8aa3b, v70
	v_mul_f32_e32 v201, 0xbfb8aa3b, v71
	v_exp_f32_e32 v194, v194
	v_exp_f32_e32 v195, v195
	v_exp_f32_e32 v196, v196
	v_exp_f32_e32 v197, v197
	v_exp_f32_e32 v198, v198
	v_exp_f32_e32 v199, v199
	v_exp_f32_e32 v200, v200
	v_exp_f32_e32 v201, v201
	v_add_f32_e32 v194, 1.0, v194
	v_add_f32_e32 v195, 1.0, v195
	v_add_f32_e32 v196, 1.0, v196
	v_add_f32_e32 v197, 1.0, v197
	v_add_f32_e32 v198, 1.0, v198
	v_add_f32_e32 v199, 1.0, v199
	v_add_f32_e32 v200, 1.0, v200
	v_add_f32_e32 v201, 1.0, v201
	v_rcp_f32_e32 v194, v194
	v_rcp_f32_e32 v195, v195
	v_rcp_f32_e32 v196, v196
	v_rcp_f32_e32 v197, v197
	v_rcp_f32_e32 v198, v198
	v_rcp_f32_e32 v199, v199
	v_rcp_f32_e32 v200, v200
	v_rcp_f32_e32 v201, v201
	v_pk_mul_f32 v[76:77], v[76:77], v[194:195]
	v_pk_mul_f32 v[78:79], v[78:79], v[196:197]
	v_pk_mul_f32 v[68:69], v[68:69], v[198:199]
	v_pk_mul_f32 v[70:71], v[70:71], v[200:201]
	v_pk_mul_f32 v[76:77], v[72:73], v[76:77]
	v_pk_mul_f32 v[78:79], v[74:75], v[78:79]
	v_pk_mul_f32 v[68:69], v[64:65], v[68:69]
	v_pk_mul_f32 v[70:71], v[66:67], v[70:71]
	v_cvt_pk_bf16_f32 v64, v76, v77
	v_cvt_pk_bf16_f32 v65, v78, v79
	v_cvt_pk_bf16_f32 v66, v68, v69
	v_cvt_pk_bf16_f32 v67, v70, v71
	global_store_dwordx4 v207, v[64:67], s[82:83]
	s_waitcnt lgkmcnt(3)
	v_pk_mul_f32 v[60:61], v[60:61], v[172:173] op_sel_hi:[1,0]
	v_pk_mul_f32 v[62:63], v[62:63], v[172:173] op_sel_hi:[1,0]
	v_pk_mul_f32 v[52:53], v[52:53], v[172:173] op_sel_hi:[1,0]
	v_pk_mul_f32 v[54:55], v[54:55], v[172:173] op_sel_hi:[1,0]
	v_pk_mul_f32 v[56:57], v[56:57], v[172:173] op_sel_hi:[1,0]
	v_pk_mul_f32 v[58:59], v[58:59], v[172:173] op_sel_hi:[1,0]
	v_pk_mul_f32 v[48:49], v[48:49], v[172:173] op_sel_hi:[1,0]
	v_pk_mul_f32 v[50:51], v[50:51], v[172:173] op_sel_hi:[1,0]
	v_mul_f32_e32 v186, 0xbfb8aa3b, v60
	v_mul_f32_e32 v187, 0xbfb8aa3b, v61
	v_mul_f32_e32 v188, 0xbfb8aa3b, v62
	v_mul_f32_e32 v189, 0xbfb8aa3b, v63
	v_mul_f32_e32 v190, 0xbfb8aa3b, v52
	v_mul_f32_e32 v191, 0xbfb8aa3b, v53
	v_mul_f32_e32 v192, 0xbfb8aa3b, v54
	v_mul_f32_e32 v193, 0xbfb8aa3b, v55
	v_exp_f32_e32 v186, v186
	v_exp_f32_e32 v187, v187
	v_exp_f32_e32 v188, v188
	v_exp_f32_e32 v189, v189
	v_exp_f32_e32 v190, v190
	v_exp_f32_e32 v191, v191
	v_exp_f32_e32 v192, v192
	v_exp_f32_e32 v193, v193
	v_add_f32_e32 v186, 1.0, v186
	v_add_f32_e32 v187, 1.0, v187
	v_add_f32_e32 v188, 1.0, v188
	v_add_f32_e32 v189, 1.0, v189
	v_add_f32_e32 v190, 1.0, v190
	v_add_f32_e32 v191, 1.0, v191
	v_add_f32_e32 v192, 1.0, v192
	v_add_f32_e32 v193, 1.0, v193
	v_rcp_f32_e32 v186, v186
	v_rcp_f32_e32 v187, v187
	v_rcp_f32_e32 v188, v188
	v_rcp_f32_e32 v189, v189
	v_rcp_f32_e32 v190, v190
	v_rcp_f32_e32 v191, v191
	v_rcp_f32_e32 v192, v192
	v_rcp_f32_e32 v193, v193
	v_pk_mul_f32 v[60:61], v[60:61], v[186:187]
	v_pk_mul_f32 v[62:63], v[62:63], v[188:189]
	v_pk_mul_f32 v[52:53], v[52:53], v[190:191]
	v_pk_mul_f32 v[54:55], v[54:55], v[192:193]
	v_pk_mul_f32 v[60:61], v[56:57], v[60:61]
	v_pk_mul_f32 v[62:63], v[58:59], v[62:63]
	v_pk_mul_f32 v[52:53], v[48:49], v[52:53]
	v_pk_mul_f32 v[54:55], v[50:51], v[54:55]
	v_cvt_pk_bf16_f32 v48, v60, v61
	v_cvt_pk_bf16_f32 v49, v62, v63
	v_cvt_pk_bf16_f32 v50, v52, v53
	v_cvt_pk_bf16_f32 v51, v54, v55
	global_store_dwordx4 v208, v[48:51], s[82:83]
	s_waitcnt lgkmcnt(2)
	v_pk_mul_f32 v[44:45], v[44:45], v[174:175] op_sel_hi:[1,0]
	v_pk_mul_f32 v[46:47], v[46:47], v[174:175] op_sel_hi:[1,0]
	v_pk_mul_f32 v[36:37], v[36:37], v[174:175] op_sel_hi:[1,0]
	v_pk_mul_f32 v[38:39], v[38:39], v[174:175] op_sel_hi:[1,0]
	v_pk_mul_f32 v[40:41], v[40:41], v[174:175] op_sel_hi:[1,0]
	v_pk_mul_f32 v[42:43], v[42:43], v[174:175] op_sel_hi:[1,0]
	v_pk_mul_f32 v[32:33], v[32:33], v[174:175] op_sel_hi:[1,0]
	v_pk_mul_f32 v[34:35], v[34:35], v[174:175] op_sel_hi:[1,0]
	v_mul_f32_e32 v194, 0xbfb8aa3b, v44
	v_mul_f32_e32 v195, 0xbfb8aa3b, v45
	v_mul_f32_e32 v196, 0xbfb8aa3b, v46
	v_mul_f32_e32 v197, 0xbfb8aa3b, v47
	v_mul_f32_e32 v198, 0xbfb8aa3b, v36
	v_mul_f32_e32 v199, 0xbfb8aa3b, v37
	v_mul_f32_e32 v200, 0xbfb8aa3b, v38
	v_mul_f32_e32 v201, 0xbfb8aa3b, v39
	v_exp_f32_e32 v194, v194
	v_exp_f32_e32 v195, v195
	v_exp_f32_e32 v196, v196
	v_exp_f32_e32 v197, v197
	v_exp_f32_e32 v198, v198
	v_exp_f32_e32 v199, v199
	v_exp_f32_e32 v200, v200
	v_exp_f32_e32 v201, v201
	v_add_f32_e32 v194, 1.0, v194
	v_add_f32_e32 v195, 1.0, v195
	v_add_f32_e32 v196, 1.0, v196
	v_add_f32_e32 v197, 1.0, v197
	v_add_f32_e32 v198, 1.0, v198
	v_add_f32_e32 v199, 1.0, v199
	v_add_f32_e32 v200, 1.0, v200
	v_add_f32_e32 v201, 1.0, v201
	v_rcp_f32_e32 v194, v194
	v_rcp_f32_e32 v195, v195
	v_rcp_f32_e32 v196, v196
	v_rcp_f32_e32 v197, v197
	v_rcp_f32_e32 v198, v198
	v_rcp_f32_e32 v199, v199
	v_rcp_f32_e32 v200, v200
	v_rcp_f32_e32 v201, v201
	v_pk_mul_f32 v[44:45], v[44:45], v[194:195]
	v_pk_mul_f32 v[46:47], v[46:47], v[196:197]
	v_pk_mul_f32 v[36:37], v[36:37], v[198:199]
	v_pk_mul_f32 v[38:39], v[38:39], v[200:201]
	v_pk_mul_f32 v[44:45], v[40:41], v[44:45]
	v_pk_mul_f32 v[46:47], v[42:43], v[46:47]
	v_pk_mul_f32 v[36:37], v[32:33], v[36:37]
	v_pk_mul_f32 v[38:39], v[34:35], v[38:39]
	v_cvt_pk_bf16_f32 v32, v44, v45
	v_cvt_pk_bf16_f32 v33, v46, v47
	v_cvt_pk_bf16_f32 v34, v36, v37
	v_cvt_pk_bf16_f32 v35, v38, v39
	global_store_dwordx4 v209, v[32:35], s[82:83]
	s_waitcnt lgkmcnt(1)
	v_pk_mul_f32 v[28:29], v[28:29], v[176:177] op_sel_hi:[1,0]
	v_pk_mul_f32 v[30:31], v[30:31], v[176:177] op_sel_hi:[1,0]
	v_pk_mul_f32 v[20:21], v[20:21], v[176:177] op_sel_hi:[1,0]
	v_pk_mul_f32 v[22:23], v[22:23], v[176:177] op_sel_hi:[1,0]
	v_pk_mul_f32 v[24:25], v[24:25], v[176:177] op_sel_hi:[1,0]
	v_pk_mul_f32 v[26:27], v[26:27], v[176:177] op_sel_hi:[1,0]
	v_pk_mul_f32 v[16:17], v[16:17], v[176:177] op_sel_hi:[1,0]
	v_pk_mul_f32 v[18:19], v[18:19], v[176:177] op_sel_hi:[1,0]
	v_mul_f32_e32 v186, 0xbfb8aa3b, v28
	v_mul_f32_e32 v187, 0xbfb8aa3b, v29
	v_mul_f32_e32 v188, 0xbfb8aa3b, v30
	v_mul_f32_e32 v189, 0xbfb8aa3b, v31
	v_mul_f32_e32 v190, 0xbfb8aa3b, v20
	v_mul_f32_e32 v191, 0xbfb8aa3b, v21
	v_mul_f32_e32 v192, 0xbfb8aa3b, v22
	v_mul_f32_e32 v193, 0xbfb8aa3b, v23
	v_exp_f32_e32 v186, v186
	v_exp_f32_e32 v187, v187
	v_exp_f32_e32 v188, v188
	v_exp_f32_e32 v189, v189
	v_exp_f32_e32 v190, v190
	v_exp_f32_e32 v191, v191
	v_exp_f32_e32 v192, v192
	v_exp_f32_e32 v193, v193
	v_add_f32_e32 v186, 1.0, v186
	v_add_f32_e32 v187, 1.0, v187
	v_add_f32_e32 v188, 1.0, v188
	v_add_f32_e32 v189, 1.0, v189
	v_add_f32_e32 v190, 1.0, v190
	v_add_f32_e32 v191, 1.0, v191
	v_add_f32_e32 v192, 1.0, v192
	v_add_f32_e32 v193, 1.0, v193
	v_rcp_f32_e32 v186, v186
	v_rcp_f32_e32 v187, v187
	v_rcp_f32_e32 v188, v188
	v_rcp_f32_e32 v189, v189
	v_rcp_f32_e32 v190, v190
	v_rcp_f32_e32 v191, v191
	v_rcp_f32_e32 v192, v192
	v_rcp_f32_e32 v193, v193
	v_pk_mul_f32 v[28:29], v[28:29], v[186:187]
	v_pk_mul_f32 v[30:31], v[30:31], v[188:189]
	v_pk_mul_f32 v[20:21], v[20:21], v[190:191]
	v_pk_mul_f32 v[22:23], v[22:23], v[192:193]
	v_pk_mul_f32 v[28:29], v[24:25], v[28:29]
	v_pk_mul_f32 v[30:31], v[26:27], v[30:31]
	v_pk_mul_f32 v[20:21], v[16:17], v[20:21]
	v_pk_mul_f32 v[22:23], v[18:19], v[22:23]
	v_cvt_pk_bf16_f32 v16, v28, v29
	v_cvt_pk_bf16_f32 v17, v30, v31
	v_cvt_pk_bf16_f32 v18, v20, v21
	v_cvt_pk_bf16_f32 v19, v22, v23
	global_store_dwordx4 v210, v[16:19], s[82:83]
	s_waitcnt lgkmcnt(0)
	v_pk_mul_f32 v[12:13], v[12:13], v[178:179] op_sel_hi:[1,0]
	v_pk_mul_f32 v[14:15], v[14:15], v[178:179] op_sel_hi:[1,0]
	v_pk_mul_f32 v[4:5], v[4:5], v[178:179] op_sel_hi:[1,0]
	v_pk_mul_f32 v[6:7], v[6:7], v[178:179] op_sel_hi:[1,0]
	v_pk_mul_f32 v[8:9], v[8:9], v[178:179] op_sel_hi:[1,0]
	v_pk_mul_f32 v[10:11], v[10:11], v[178:179] op_sel_hi:[1,0]
	v_pk_mul_f32 v[0:1], v[0:1], v[178:179] op_sel_hi:[1,0]
	v_pk_mul_f32 v[2:3], v[2:3], v[178:179] op_sel_hi:[1,0]
	v_mul_f32_e32 v194, 0xbfb8aa3b, v12
	v_mul_f32_e32 v195, 0xbfb8aa3b, v13
	v_mul_f32_e32 v196, 0xbfb8aa3b, v14
	v_mul_f32_e32 v197, 0xbfb8aa3b, v15
	v_mul_f32_e32 v198, 0xbfb8aa3b, v4
	v_mul_f32_e32 v199, 0xbfb8aa3b, v5
	v_mul_f32_e32 v200, 0xbfb8aa3b, v6
	v_mul_f32_e32 v201, 0xbfb8aa3b, v7
	v_exp_f32_e32 v194, v194
	v_exp_f32_e32 v195, v195
	v_exp_f32_e32 v196, v196
	v_exp_f32_e32 v197, v197
	v_exp_f32_e32 v198, v198
	v_exp_f32_e32 v199, v199
	v_exp_f32_e32 v200, v200
	v_exp_f32_e32 v201, v201
	v_add_f32_e32 v194, 1.0, v194
	v_add_f32_e32 v195, 1.0, v195
	v_add_f32_e32 v196, 1.0, v196
	v_add_f32_e32 v197, 1.0, v197
	v_add_f32_e32 v198, 1.0, v198
	v_add_f32_e32 v199, 1.0, v199
	v_add_f32_e32 v200, 1.0, v200
	v_add_f32_e32 v201, 1.0, v201
	v_rcp_f32_e32 v194, v194
	v_rcp_f32_e32 v195, v195
	v_rcp_f32_e32 v196, v196
	v_rcp_f32_e32 v197, v197
	v_rcp_f32_e32 v198, v198
	v_rcp_f32_e32 v199, v199
	v_rcp_f32_e32 v200, v200
	v_rcp_f32_e32 v201, v201
	v_pk_mul_f32 v[12:13], v[12:13], v[194:195]
	v_pk_mul_f32 v[14:15], v[14:15], v[196:197]
	v_pk_mul_f32 v[4:5], v[4:5], v[198:199]
	v_pk_mul_f32 v[6:7], v[6:7], v[200:201]
	v_pk_mul_f32 v[12:13], v[8:9], v[12:13]
	v_pk_mul_f32 v[14:15], v[10:11], v[14:15]
	v_pk_mul_f32 v[4:5], v[0:1], v[4:5]
	v_pk_mul_f32 v[6:7], v[2:3], v[6:7]
	v_cvt_pk_bf16_f32 v0, v12, v13
	v_cvt_pk_bf16_f32 v1, v14, v15
	v_cvt_pk_bf16_f32 v2, v4, v5
	v_cvt_pk_bf16_f32 v3, v6, v7
	global_store_dwordx4 v211, v[0:3], s[82:83]
	s_cmp_eq_u32 s98, 0
	s_cbranch_scc1 .Le5_end
	s_waitcnt vmcnt(8)
	v_add_f32_e32 v224, v224, v225
	v_add_f32_e32 v226, v226, v227
	v_add_f32_e32 v228, v228, v229
	v_add_f32_e32 v230, v230, v231
	v_add_f32_e32 v232, v232, v233
	v_add_f32_e32 v234, v234, v235
	v_add_f32_e32 v236, v236, v237
	v_add_f32_e32 v238, v238, v239
	v_add_f32_e32 v224, v224, v226
	v_add_f32_e32 v228, v228, v230
	v_add_f32_e32 v232, v232, v234
	v_add_f32_e32 v236, v236, v238
	v_add_f32_e32 v250, v224, v228
	v_add_f32_e32 v250, v250, v232
	v_add_f32_e32 v250, v250, v236
	v_fmamk_f32 v250, v250, 0x3a800000, v156
	v_add_f32_e32 v240, v240, v241
	v_add_f32_e32 v242, v242, v243
	v_add_f32_e32 v244, v244, v245
	v_add_f32_e32 v246, v246, v247
	v_add_f32_e32 v180, v180, v181
	v_add_f32_e32 v182, v182, v183
	v_add_f32_e32 v212, v212, v213
	v_add_f32_e32 v214, v214, v215
	v_add_f32_e32 v240, v240, v242
	v_add_f32_e32 v244, v244, v246
	v_add_f32_e32 v180, v180, v182
	v_add_f32_e32 v212, v212, v214
	v_add_f32_e32 v251, v240, v244
	v_add_f32_e32 v251, v251, v180
	v_add_f32_e32 v251, v251, v212
	v_fmamk_f32 v251, v251, 0x3a800000, v156
	v_rsq_f32_e32 v250, v250
	v_rsq_f32_e32 v251, v251
.Le5_end:
	s_mov_b64 s[4:5], -1
	s_cbranch_vccnz .LBB0_912
	s_and_b64 vcc, exec, s[0:1]
	s_cbranch_vccnz .LBB0_911
	s_barrier
	s_branch .LBB0_911
